# v27 plus MLA flash loop: K/V tile t+1 written to LDS after the barrier of tile t (overlaps QK MFMAs) instead of before the next barrier
# speedup vs baseline: 1.0108x; 1.0038x over previous
; #define FL_LOAD(kt, P) do { const char* kb_ = (const char*)K + (size_t)(64 * (kt)) * ldk * 2; const char* vb_ = (const char*)V + (size_t)(64 * (kt)) * ldv * 2; \
;         _Pragma("unroll") for (int j = 0; j < NKC; ++j) kr[P][j] = *(const v4u*)(kb_ + kofs[j]); \
;         _Pragma("unroll") for (int j = 0; j < NVC; ++j) vr[P][j] = *(const v4u*)(vb_ + vofs[j]); } while (0)
;     ...
;     const int lane = tid & 63, w = __builtin_amdgcn_readfirstlane(tid >> 6), qw = w & 3, kh = w >> 2, g = lane >> 4, c16 = lane & 15;
;     const int q0 = qb * 128, qbase = q0 + 32 * qw;
;     const int first2 = MODE == 0 ? 2 : ((2 * qb - 2) > 2 ? (2 * qb - 2) : 2);
;     const int nt = MODE == 0 ? 2 * qb + 1 : 1 + ((2 * qb + 2 - first2) > 0 ? (2 * qb + 2 - first2) : 0);
;     ...
;     bf16x8 qf[2][NKS];
; #pragma unroll
;     for (int sb = 0; sb < 2; ++sb)
; #pragma unroll
;         for (int ks = 0; ks < NKS; ++ks) qf[sb][ks] = *(const bf16x8*)(Q + (size_t)(qbase + 16 * sb + c16) * ldq + 32 * ks + 8 * g);
;     v4u kr[2][NKC], vr[2][NVC];
;     unsigned kofs[NKC], vofs[NVC];
; #pragma unroll
;     for (int j = 0; j < NKC; ++j) { const int c = tid + 512 * j; kofs[j] = (unsigned)(((c / KCH) * ldk + (c % KCH) * 8) * 2); }
; #pragma unroll
;     for (int j = 0; j < NVC; ++j) { const int c = tid + 512 * j; vofs[j] = (unsigned)(((c / VCH) * ldv + (c % VCH) * 8) * 2); }
;     ...
;     f32x4 acc_o[2][NDV];
; #pragma unroll
;     for (int sb = 0; sb < 2; ++sb)
; #pragma unroll
;         for (int n = 0; n < NDV; ++n) acc_o[sb][n] = (f32x4){0.f, 0.f, 0.f, 0.f};
;     float m[2] = {-1e30f, -1e30f}, l[2] = {0.f, 0.f};
;     FL_LOAD(FL_KT(0), 0);
;     if (nt > 1) FL_LOAD(FL_KT(1), 1);
;     for (int it2 = 0; it2 < nt; it2 += 2) {
; #pragma unroll
;         for (int P = 0; P < 2; ++P) {
;         const int it = it2 + P;
;         if (it < nt) {
;         const int buf = P, key0 = 64 * FL_KT(it) + 32 * kh;
;         FL_STORE(buf, P);
.LBB0_780:
	s_add_u32 s66, s9, 0x28b00100
	s_addc_u32 s67, s12, 0
	s_ashr_i32 s45, s40, 8
	v_and_b32_e32 v199, 63, v2
	v_bfe_u32 v14, v2, 4, 2
	s_lshl_b32 s68, s8, 1
	s_mul_i32 s8, s45, 0x3200
	v_lshlrev_b32_e32 v2, 3, v2
	s_movk_i32 s12, 0x190
	v_and_b32_e32 v15, 24, v2
	v_mul_lo_u32 v2, v4, s12
	s_add_i32 s8, s8, 0
	v_add_u32_e32 v16, 0, v2
	v_mul_lo_u32 v2, v5, s12
	v_mov_b32_e32 v5, s8
	v_add_u32_e32 v17, 0, v2
	v_mul_lo_u32 v2, v11, s12
	v_mad_u32_u24 v201, v3, s12, v5
	s_mul_i32 s12, s45, 0xfffff200
	s_mul_i32 s9, s45, 0x2400
	s_add_i32 s8, s8, s12
	v_lshlrev_b32_e32 v198, 2, v14
	v_lshrrev_b32_e32 v14, 2, v3
	v_add_u32_e32 v11, 0, v2
	v_mul_lo_u32 v2, v12, s96
	v_mov_b32_e32 v3, s8
	s_add_i32 s8, s92, s9
	v_or_b32_e32 v14, v198, v14
	v_add_u32_e32 v12, 0, v2
	v_mul_lo_u32 v4, v13, s96
	v_add_u32_e32 v19, s92, v2
	v_mov_b32_e32 v2, s8
	v_add_u32_e32 v13, 0, v4
	v_mad_u32_u24 v18, v14, s96, v3
	v_add_u32_e32 v20, s92, v4
	v_mad_u32_u24 v14, v14, s96, v2
	v_mov_b32_e32 v4, v1
	v_mov_b32_e32 v5, v1
	s_lshl_b32 s70, s45, 5
	v_mov_b32_e32 v2, v1
	v_mov_b32_e32 v3, v1
	v_add_u32_e32 v203, v12, v7
	v_add_u32_e32 v204, v13, v9
	v_add_u32_e32 v205, v18, v15
	v_add_u32_e32 v206, v19, v7
	v_add_u32_e32 v207, v20, v9
	v_add_u32_e32 v208, v14, v15
	v_add_u32_e32 v209, v16, v6
	v_add_u32_e32 v210, v17, v8
	v_add_u32_e32 v211, v11, v10
	v_mov_b64_e32 v[8:9], v[4:5]
	v_mov_b64_e32 v[12:13], v[4:5]
	v_mov_b64_e32 v[16:17], v[4:5]
	v_mov_b64_e32 v[20:21], v[4:5]
	v_mov_b64_e32 v[24:25], v[4:5]
	v_mov_b64_e32 v[28:29], v[4:5]
	v_mov_b64_e32 v[32:33], v[4:5]
	v_mov_b64_e32 v[36:37], v[4:5]
	v_mov_b64_e32 v[40:41], v[4:5]
	v_mov_b64_e32 v[44:45], v[4:5]
	v_mov_b64_e32 v[48:49], v[4:5]
	v_mov_b64_e32 v[52:53], v[4:5]
	v_mov_b64_e32 v[56:57], v[4:5]
	v_mov_b64_e32 v[60:61], v[4:5]
	v_mov_b64_e32 v[64:65], v[4:5]
	v_mov_b32_e32 v185, v1
	v_mov_b32_e32 v183, v1
	s_mov_b32 s79, 3
	v_or_b32_e32 v202, s70, v198
	v_mov_b32_e32 v200, 0
	v_mov_b32_e32 v187, 0xf149f2ca
	s_movk_i32 s8, 0x100
	v_mov_b64_e32 v[6:7], v[2:3]
	v_mov_b64_e32 v[10:11], v[2:3]
	v_mov_b64_e32 v[14:15], v[2:3]
	v_mov_b64_e32 v[18:19], v[2:3]
	v_mov_b64_e32 v[22:23], v[2:3]
	v_mov_b64_e32 v[26:27], v[2:3]
	v_mov_b64_e32 v[30:31], v[2:3]
	v_mov_b64_e32 v[34:35], v[2:3]
	v_mov_b64_e32 v[38:39], v[2:3]
	v_mov_b64_e32 v[42:43], v[2:3]
	v_mov_b64_e32 v[46:47], v[2:3]
	v_mov_b64_e32 v[50:51], v[2:3]
	v_mov_b64_e32 v[54:55], v[2:3]
	v_mov_b64_e32 v[58:59], v[2:3]
	v_mov_b64_e32 v[62:63], v[2:3]
	v_mov_b32_e32 v213, 0xf149f2ca
	v_mov_b32_e32 v212, 0
	s_waitcnt vmcnt(4)
	ds_write_b128 v209, v[114:117]
	s_waitcnt vmcnt(3)
	ds_write_b128 v210, v[118:121]
	s_waitcnt vmcnt(2)
	ds_write_b128 v211, v[122:125]
	s_waitcnt vmcnt(1)
	ds_write_b128 v203, v[126:129] offset:25600
	s_waitcnt vmcnt(0)
	ds_write_b128 v204, v[130:133] offset:25600
	s_branch .LBB0_783

; #define FL_LOAD(kt, P) do { const char* kb_ = (const char*)K + (size_t)(64 * (kt)) * ldk * 2; const char* vb_ = (const char*)V + (size_t)(64 * (kt)) * ldv * 2; \
;         _Pragma("unroll") for (int j = 0; j < NKC; ++j) kr[P][j] = *(const v4u*)(kb_ + kofs[j]); \
;         _Pragma("unroll") for (int j = 0; j < NVC; ++j) vr[P][j] = *(const v4u*)(vb_ + vofs[j]); } while (0)
;     ...
;     for (int it2 = 0; it2 < nt; it2 += 2) {
; #pragma unroll
;         for (int P = 0; P < 2; ++P) {
;         const int it = it2 + P;
;         if (it < nt) {
;         const int buf = P, key0 = 64 * FL_KT(it) + 32 * kh;
;         FL_STORE(buf, P);
;         __syncthreads();
;         if (it + 2 < nt) FL_LOAD(FL_KT(it + 2), P);
.LBB0_783:
	s_add_i32 s82, s79, -3
	s_cmp_le_u32 s82, s68
	s_cbranch_scc0 .LBB0_795
	s_cmp_ge_u32 s82, s68
	s_waitcnt lgkmcnt(0)
	s_barrier
	s_cbranch_scc1 .LBB0_786
	s_waitcnt vmcnt(4)
	ds_write_b128 v209, v[134:137] offset:44032
	s_waitcnt vmcnt(3)
	ds_write_b128 v210, v[138:141] offset:44032
	s_waitcnt vmcnt(2)
	ds_write_b128 v211, v[142:145] offset:44032
	s_waitcnt vmcnt(1)
	ds_write_b128 v206, v[146:149]
	s_waitcnt vmcnt(0)
	ds_write_b128 v207, v[150:153]
	s_sub_i32 s12, s8, 64
	s_ashr_i32 s13, s12, 31
	s_mul_i32 s14, s12, 0xc00
	s_mul_hi_i32 s9, s12, 0xc00
	s_add_u32 s14, s42, s14
	s_addc_u32 s15, s43, s9
	s_lshl_b64 s[12:13], s[12:13], 12
	s_add_u32 s12, s66, s12
	s_addc_u32 s13, s67, s13
	v_lshl_add_u64 v[114:115], s[14:15], 0, v[0:1]
	v_lshl_add_u64 v[118:119], s[14:15], 0, v[188:189]
	v_lshl_add_u64 v[122:123], s[14:15], 0, v[190:191]
	v_lshl_add_u64 v[126:127], s[12:13], 0, v[192:193]
	v_lshl_add_u64 v[130:131], s[12:13], 0, v[194:195]
	global_load_dwordx4 v[114:117], v[114:115], off
	s_nop 0
	global_load_dwordx4 v[118:121], v[118:119], off
	s_nop 0
	global_load_dwordx4 v[122:125], v[122:123], off
	s_nop 0
	global_load_dwordx4 v[126:129], v[126:127], off
	s_nop 0
	global_load_dwordx4 v[130:133], v[130:131], off

; #define FL_LOAD(kt, P) do { const char* kb_ = (const char*)K + (size_t)(64 * (kt)) * ldk * 2; const char* vb_ = (const char*)V + (size_t)(64 * (kt)) * ldv * 2; \
;         _Pragma("unroll") for (int j = 0; j < NKC; ++j) kr[P][j] = *(const v4u*)(kb_ + kofs[j]); \
;         _Pragma("unroll") for (int j = 0; j < NVC; ++j) vr[P][j] = *(const v4u*)(vb_ + vofs[j]); } while (0)
;     ...
;     for (int it2 = 0; it2 < nt; it2 += 2) {
; #pragma unroll
;         for (int P = 0; P < 2; ++P) {
;         const int it = it2 + P;
;         if (it < nt) {
;         const int buf = P, key0 = 64 * FL_KT(it) + 32 * kh;
;         FL_STORE(buf, P);
;         __syncthreads();
;         if (it + 2 < nt) FL_LOAD(FL_KT(it + 2), P);
.LBB0_796:
	s_cmp_gt_u32 s79, s68
	s_waitcnt lgkmcnt(0)
	s_barrier
	s_waitcnt vmcnt(4)
	ds_write_b128 v209, v[114:117]
	s_waitcnt vmcnt(3)
	ds_write_b128 v210, v[118:121]
	s_waitcnt vmcnt(2)
	ds_write_b128 v211, v[122:125]
	s_waitcnt vmcnt(1)
	ds_write_b128 v203, v[126:129] offset:25600
	s_waitcnt vmcnt(0)
	ds_write_b128 v204, v[130:133] offset:25600
	s_cbranch_scc1 .LBB0_798
	s_ashr_i32 s9, s8, 31
	s_mul_i32 s12, s8, 0xc00
	s_mul_hi_i32 s13, s8, 0xc00
	s_add_u32 s12, s42, s12
	s_addc_u32 s13, s43, s13
	s_lshl_b64 s[14:15], s[8:9], 12
	v_lshl_add_u64 v[134:135], s[12:13], 0, v[0:1]
	v_lshl_add_u64 v[138:139], s[12:13], 0, v[188:189]
	v_lshl_add_u64 v[142:143], s[12:13], 0, v[190:191]
	s_add_u32 s12, s66, s14
	s_addc_u32 s13, s67, s15
	v_lshl_add_u64 v[146:147], s[12:13], 0, v[192:193]
	v_lshl_add_u64 v[150:151], s[12:13], 0, v[194:195]
	global_load_dwordx4 v[134:137], v[134:135], off
	s_nop 0
	global_load_dwordx4 v[138:141], v[138:139], off
	s_nop 0
	global_load_dwordx4 v[142:145], v[142:143], off
	s_nop 0
	global_load_dwordx4 v[146:149], v[146:147], off
	s_nop 0
	global_load_dwordx4 v[150:153], v[150:151], off
